# relaxed first-K-tile waits and cached tile coordinates extended to the R1/R4 GEMM loops
# speedup vs baseline: 1.0046x; 1.0046x over previous
; #define PG8_STAGE(bufoff, gbase, voff, p64) do { _Pragma("unroll") for (int _i = 0; _i < 2; ++_i) { \
;         const char* _gb = (const char*)(gbase) + (size_t)_i * (p64); const unsigned _la = ldsbase + (unsigned)(bufoff) + (unsigned)_i * 8192u; \
;         asm volatile("s_mov_b32 m0, %0\n\ts_nop 0\n\tglobal_load_lds_dwordx4 %1, %2" :: "s"(_la), "v"(voff), "s"(_gb) : "memory"); } } while (0)
; #define PG8_LDA(dst, b, h) do { _Pragma("unroll") for (int m = 0; m < 4; ++m) _Pragma("unroll") for (int k = 0; k < 2; ++k) dst[m][k] = *(const LAS bf16x8*)(lds + PG8_SA(b, h) + aoff + m * 2048 + k * 1024); } while (0)
; #define PG8_LDB(dst, b, h) do { _Pragma("unroll") for (int n = 0; n < 2; ++n) _Pragma("unroll") for (int k = 0; k < 2; ++k) dst[n][k] = *(const LAS bf16x8*)(lds + PG8_SB(b, h) + boff + n * 2048 + k * 1024); } while (0)
; #define PG8_MMA(ai, bj, At, Bt) do { __builtin_amdgcn_s_setprio(1); _Pragma("unroll") for (int m = 0; m < 4; ++m) _Pragma("unroll") for (int n = 0; n < 2; ++n) _Pragma("unroll") for (int k = 0; k < 2; ++k) \
;         acc[ai][bj][m][n] = __builtin_amdgcn_mfma_f32_16x16x32_bf16(Bt[n][k], At[m][k], acc[ai][bj][m][n], 0, 0, 0); __builtin_amdgcn_s_setprio(0); } while (0)
; #define PG8_WAIT_V(n) asm volatile("s_waitcnt vmcnt(" #n ")" ::: "memory")
; #define PG8_WAIT_L(n) asm volatile("s_waitcnt lgkmcnt(" #n ")" ::: "memory")
; #define PG8_BAR __builtin_amdgcn_s_barrier()
; #define PG8_SCHED __builtin_amdgcn_sched_barrier(0)
; template <class Epi, class Sched>
; __device__ __forceinline__ void gemm_phase(LAS unsigned char* lds, const Sched& S, const Epi& E) {
;     ...
;             PG8_LDB(B0, 0, 0); PG8_LDB(B1, 0, 1); PG8_SCHED; PG8_LDA(At, 0, 0); PG8_STAGE(PG8_SA(1, 1), a1 + hA, voffA, hA / 2);
;             PG8_WAIT_V(8); PG8_WAIT_L(0); PG8_BAR; PG8_MMA(0, 0, At, B0); PG8_MMA(0, 1, At, B1); PG8_BAR; PG8_SCHED;
.LBB0_552:
	s_add_u32 s74, s22, 0x40080
	s_addc_u32 s75, s23, 0
	s_add_u32 s57, s16, 0x100
	s_addc_u32 s80, s17, 0
	s_mov_b32 s81, -2
	s_waitcnt vmcnt(2)
	s_waitcnt vmcnt(0)
	v_add_u32_e32 v128, 0x10000, v154
	ds_read_b128 v[138:141], v128
	ds_read_b128 v[142:145], v128 offset:1024
	ds_read_b128 v[146:149], v128 offset:2048
	ds_read_b128 v[172:175], v128 offset:3072
	v_add_u32_e32 v128, 0x14000, v154
	ds_read_b128 v[178:181], v128
	ds_read_b128 v[182:185], v128 offset:1024
	ds_read_b128 v[186:189], v128 offset:2048
	ds_read_b128 v[190:193], v128 offset:3072
	s_add_u32 s16, s74, 0xfffc0080
	s_addc_u32 s17, s75, -1
	s_cmp_eq_u32 s81, 12
	s_cselect_b32 s16, s58, s16
	s_cselect_b32 s17, s59, s17
	s_cselect_b32 s76, s62, s57
	s_cselect_b32 s77, s63, s80
	s_add_u32 s22, s16, 0x80
	s_addc_u32 s23, s17, 0
	ds_read_b128 v[194:197], v155
	ds_read_b128 v[198:201], v155 offset:1024
	ds_read_b128 v[202:205], v155 offset:2048
	ds_read_b128 v[206:209], v155 offset:3072
	ds_read_b128 v[210:213], v155 offset:4096
	ds_read_b128 v[214:217], v155 offset:5120
	ds_read_b128 v[218:221], v155 offset:6144
	ds_read_b128 v[222:225], v155 offset:7168
	s_mov_b32 m0, s67
	s_nop 0
	global_load_lds_dwordx4 v150, s[74:75]
	s_add_u32 s82, s74, 0x20000
	s_mov_b32 m0, s69
	s_addc_u32 s83, s75, 0
	global_load_lds_dwordx4 v150, s[82:83]
	s_cmp_eq_u32 s20, 0
	s_cbranch_scc1 .Lpeel_strict_11572_1
	s_waitcnt vmcnt(16) lgkmcnt(0)
	s_branch .Lpeel_join_11572_1

; #define PG8_STAGE(bufoff, gbase, voff, p64) do { _Pragma("unroll") for (int _i = 0; _i < 2; ++_i) { \
;         const char* _gb = (const char*)(gbase) + (size_t)_i * (p64); const unsigned _la = ldsbase + (unsigned)(bufoff) + (unsigned)_i * 8192u; \
;         asm volatile("s_mov_b32 m0, %0\n\ts_nop 0\n\tglobal_load_lds_dwordx4 %1, %2" :: "s"(_la), "v"(voff), "s"(_gb) : "memory"); } } while (0)
; #define PG8_LDA(dst, b, h) do { _Pragma("unroll") for (int m = 0; m < 4; ++m) _Pragma("unroll") for (int k = 0; k < 2; ++k) dst[m][k] = *(const LAS bf16x8*)(lds + PG8_SA(b, h) + aoff + m * 2048 + k * 1024); } while (0)
; #define PG8_MMA(ai, bj, At, Bt) do { __builtin_amdgcn_s_setprio(1); _Pragma("unroll") for (int m = 0; m < 4; ++m) _Pragma("unroll") for (int n = 0; n < 2; ++n) _Pragma("unroll") for (int k = 0; k < 2; ++k) \
;         acc[ai][bj][m][n] = __builtin_amdgcn_mfma_f32_16x16x32_bf16(Bt[n][k], At[m][k], acc[ai][bj][m][n], 0, 0, 0); __builtin_amdgcn_s_setprio(0); } while (0)
; #define PG8_WAIT_V(n) asm volatile("s_waitcnt vmcnt(" #n ")" ::: "memory")
; #define PG8_WAIT_L(n) asm volatile("s_waitcnt lgkmcnt(" #n ")" ::: "memory")
; #define PG8_BAR __builtin_amdgcn_s_barrier()
; #define PG8_SCHED __builtin_amdgcn_sched_barrier(0)
; template <class Epi, class Sched>
; __device__ __forceinline__ void gemm_phase(LAS unsigned char* lds, const Sched& S, const Epi& E) {
;     ...
;             PG8_WAIT_V(8); PG8_WAIT_L(0); PG8_BAR; PG8_MMA(0, 0, At, B0); PG8_MMA(0, 1, At, B1); PG8_BAR; PG8_SCHED;
;             PG8_LDA(At, 0, 1); PG8_STAGE(PG8_SB(0, 0), b2, vB2, hB2 / 2); PG8_STAGE(PG8_SB(0, 1), b2 + hB2, vB2, hB2 / 2); PG8_STAGE(PG8_SA(0, 0), a2, vA2, hA2 / 2);
;             PG8_WAIT_V(8); PG8_WAIT_L(0); PG8_BAR; PG8_MMA(1, 0, At, B0); PG8_MMA(1, 1, At, B1); PG8_BAR; PG8_SCHED;
.Lpeel_join_11572_1:
	s_barrier
	v_mfma_f32_16x16x32_bf16 v[124:127], v[138:141], v[194:197], 0
	v_mfma_f32_16x16x32_bf16 v[120:123], v[146:149], v[194:197], 0
	v_mfma_f32_16x16x32_bf16 v[112:115], v[138:141], v[202:205], 0
	v_mfma_f32_16x16x32_bf16 v[104:107], v[146:149], v[202:205], 0
	v_mfma_f32_16x16x32_bf16 v[96:99], v[138:141], v[210:213], 0
	v_mfma_f32_16x16x32_bf16 v[88:91], v[146:149], v[210:213], 0
	v_mfma_f32_16x16x32_bf16 v[80:83], v[138:141], v[218:221], 0
	v_mfma_f32_16x16x32_bf16 v[72:75], v[146:149], v[218:221], 0
	v_mfma_f32_16x16x32_bf16 v[124:127], v[142:145], v[198:201], v[124:127]
	v_mfma_f32_16x16x32_bf16 v[120:123], v[172:175], v[198:201], v[120:123]
	v_mfma_f32_16x16x32_bf16 v[112:115], v[142:145], v[206:209], v[112:115]
	v_mfma_f32_16x16x32_bf16 v[104:107], v[172:175], v[206:209], v[104:107]
	v_mfma_f32_16x16x32_bf16 v[96:99], v[142:145], v[214:217], v[96:99]
	v_mfma_f32_16x16x32_bf16 v[88:91], v[172:175], v[214:217], v[88:91]
	v_mfma_f32_16x16x32_bf16 v[80:83], v[142:145], v[222:225], v[80:83]
	v_mfma_f32_16x16x32_bf16 v[72:75], v[172:175], v[222:225], v[72:75]
	v_mfma_f32_16x16x32_bf16 v[116:119], v[178:181], v[194:197], 0
	v_mfma_f32_16x16x32_bf16 v[108:111], v[186:189], v[194:197], 0
	v_mfma_f32_16x16x32_bf16 v[100:103], v[178:181], v[202:205], 0
	v_mfma_f32_16x16x32_bf16 v[92:95], v[186:189], v[202:205], 0
	v_mfma_f32_16x16x32_bf16 v[84:87], v[178:181], v[210:213], 0
	v_mfma_f32_16x16x32_bf16 v[76:79], v[186:189], v[210:213], 0
	v_mfma_f32_16x16x32_bf16 v[68:71], v[178:181], v[218:221], 0
	v_mfma_f32_16x16x32_bf16 v[64:67], v[186:189], v[218:221], 0
	v_mfma_f32_16x16x32_bf16 v[116:119], v[182:185], v[198:201], v[116:119]
	v_mfma_f32_16x16x32_bf16 v[108:111], v[190:193], v[198:201], v[108:111]
	v_mfma_f32_16x16x32_bf16 v[100:103], v[182:185], v[206:209], v[100:103]
	v_mfma_f32_16x16x32_bf16 v[92:95], v[190:193], v[206:209], v[92:95]
	v_mfma_f32_16x16x32_bf16 v[84:87], v[182:185], v[214:217], v[84:87]
	v_mfma_f32_16x16x32_bf16 v[76:79], v[190:193], v[214:217], v[76:79]
	v_mfma_f32_16x16x32_bf16 v[68:71], v[182:185], v[222:225], v[68:71]
	v_mfma_f32_16x16x32_bf16 v[64:67], v[190:193], v[222:225], v[64:67]
	s_add_i32 s81, s81, 2
	s_add_u32 s74, s74, 0x100
	s_addc_u32 s75, s75, 0
	s_add_u32 s57, s57, 0x100
	s_addc_u32 s80, s80, 0
	s_barrier
	s_add_u32 s82, s76, 0x20000
	ds_read_b128 v[194:197], v155 offset:16384
	ds_read_b128 v[198:201], v155 offset:17408
	ds_read_b128 v[202:205], v155 offset:18432
	ds_read_b128 v[206:209], v155 offset:19456
	ds_read_b128 v[210:213], v155 offset:20480
	ds_read_b128 v[214:217], v155 offset:21504
	ds_read_b128 v[218:221], v155 offset:22528
	ds_read_b128 v[222:225], v155 offset:23552
	s_mov_b32 m0, s24
	s_nop 0
	global_load_lds_dwordx4 v151, s[76:77]
	s_mov_b32 m0, s33
	s_addc_u32 s83, s77, 0
	global_load_lds_dwordx4 v151, s[82:83]
	s_add_u32 s82, s76, 0x40000
	s_mov_b32 m0, s34
	s_addc_u32 s83, s77, 0
	global_load_lds_dwordx4 v151, s[82:83]
	s_add_u32 s82, s76, 0x60000
	s_mov_b32 m0, s35
	s_addc_u32 s83, s77, 0
	global_load_lds_dwordx4 v151, s[82:83]
	s_mov_b32 m0, s15
	s_nop 0
	global_load_lds_dwordx4 v150, s[16:17]
	s_add_u32 s82, s16, 0x20000
	s_mov_b32 m0, s36
	s_addc_u32 s83, s17, 0
	global_load_lds_dwordx4 v150, s[82:83]
	s_cmp_eq_u32 s20, 0
	s_cbranch_scc1 .Lpeel_strict_11572_0
	s_waitcnt vmcnt(16) lgkmcnt(0)
	s_branch .Lpeel_join_11572_0

; #define PG8_STAGE(bufoff, gbase, voff, p64) do { _Pragma("unroll") for (int _i = 0; _i < 2; ++_i) { \
;         const char* _gb = (const char*)(gbase) + (size_t)_i * (p64); const unsigned _la = ldsbase + (unsigned)(bufoff) + (unsigned)_i * 8192u; \
;         asm volatile("s_mov_b32 m0, %0\n\ts_nop 0\n\tglobal_load_lds_dwordx4 %1, %2" :: "s"(_la), "v"(voff), "s"(_gb) : "memory"); } } while (0)
; #define PG8_LDA(dst, b, h) do { _Pragma("unroll") for (int m = 0; m < 4; ++m) _Pragma("unroll") for (int k = 0; k < 2; ++k) dst[m][k] = *(const LAS bf16x8*)(lds + PG8_SA(b, h) + aoff + m * 2048 + k * 1024); } while (0)
; #define PG8_MMA(ai, bj, At, Bt) do { __builtin_amdgcn_s_setprio(1); _Pragma("unroll") for (int m = 0; m < 4; ++m) _Pragma("unroll") for (int n = 0; n < 2; ++n) _Pragma("unroll") for (int k = 0; k < 2; ++k) \
;         acc[ai][bj][m][n] = __builtin_amdgcn_mfma_f32_16x16x32_bf16(Bt[n][k], At[m][k], acc[ai][bj][m][n], 0, 0, 0); __builtin_amdgcn_s_setprio(0); } while (0)
; #define PG8_WAIT_V(n) asm volatile("s_waitcnt vmcnt(" #n ")" ::: "memory")
; #define PG8_WAIT_L(n) asm volatile("s_waitcnt lgkmcnt(" #n ")" ::: "memory")
; #define PG8_BAR __builtin_amdgcn_s_barrier()
; #define PG8_SCHED __builtin_amdgcn_sched_barrier(0)
; template <class Epi, class Sched>
; __device__ __forceinline__ void gemm_phase(LAS unsigned char* lds, const Sched& S, const Epi& E) {
;     ...
;             PG8_WAIT_V(8); PG8_WAIT_L(0); PG8_BAR; PG8_MMA(0, 0, At, B0); PG8_MMA(0, 1, At, B1); PG8_BAR; PG8_SCHED;
;             PG8_LDA(At, 0, 1); PG8_STAGE(PG8_SB(0, 0), b2, vB2, hB2 / 2); PG8_STAGE(PG8_SB(0, 1), b2 + hB2, vB2, hB2 / 2); PG8_STAGE(PG8_SA(0, 0), a2, vA2, hA2 / 2);
;             PG8_WAIT_V(8); PG8_WAIT_L(0); PG8_BAR; PG8_MMA(1, 0, At, B0); PG8_MMA(1, 1, At, B1); PG8_BAR; PG8_SCHED;
.Lpeel_join_11572_0:
	s_barrier
	v_mfma_f32_16x16x32_bf16 v[60:63], v[138:141], v[194:197], 0
	v_mfma_f32_16x16x32_bf16 v[56:59], v[146:149], v[194:197], 0
	v_mfma_f32_16x16x32_bf16 v[48:51], v[138:141], v[202:205], 0
	v_mfma_f32_16x16x32_bf16 v[40:43], v[146:149], v[202:205], 0
	v_mfma_f32_16x16x32_bf16 v[32:35], v[138:141], v[210:213], 0
	v_mfma_f32_16x16x32_bf16 v[24:27], v[146:149], v[210:213], 0
	v_mfma_f32_16x16x32_bf16 v[16:19], v[138:141], v[218:221], 0
	v_mfma_f32_16x16x32_bf16 v[8:11], v[146:149], v[218:221], 0
	v_mfma_f32_16x16x32_bf16 v[60:63], v[142:145], v[198:201], v[60:63]
	v_mfma_f32_16x16x32_bf16 v[56:59], v[172:175], v[198:201], v[56:59]
	v_mfma_f32_16x16x32_bf16 v[48:51], v[142:145], v[206:209], v[48:51]
	v_mfma_f32_16x16x32_bf16 v[40:43], v[172:175], v[206:209], v[40:43]
	v_mfma_f32_16x16x32_bf16 v[32:35], v[142:145], v[214:217], v[32:35]
	v_mfma_f32_16x16x32_bf16 v[24:27], v[172:175], v[214:217], v[24:27]
	v_mfma_f32_16x16x32_bf16 v[16:19], v[142:145], v[222:225], v[16:19]
	v_mfma_f32_16x16x32_bf16 v[8:11], v[172:175], v[222:225], v[8:11]
	v_mfma_f32_16x16x32_bf16 v[52:55], v[178:181], v[194:197], 0
	v_mfma_f32_16x16x32_bf16 v[44:47], v[186:189], v[194:197], 0
	v_mfma_f32_16x16x32_bf16 v[36:39], v[178:181], v[202:205], 0
	v_mfma_f32_16x16x32_bf16 v[28:31], v[186:189], v[202:205], 0
	v_mfma_f32_16x16x32_bf16 v[20:23], v[178:181], v[210:213], 0
	v_mfma_f32_16x16x32_bf16 v[12:15], v[186:189], v[210:213], 0
	v_mfma_f32_16x16x32_bf16 v[4:7], v[178:181], v[218:221], 0
	v_mfma_f32_16x16x32_bf16 v[0:3], v[186:189], v[218:221], 0
	v_mfma_f32_16x16x32_bf16 v[52:55], v[182:185], v[198:201], v[52:55]
	v_mfma_f32_16x16x32_bf16 v[44:47], v[190:193], v[198:201], v[44:47]
	v_mfma_f32_16x16x32_bf16 v[36:39], v[182:185], v[206:209], v[36:39]
	v_mfma_f32_16x16x32_bf16 v[28:31], v[190:193], v[206:209], v[28:31]
	v_mfma_f32_16x16x32_bf16 v[20:23], v[182:185], v[214:217], v[20:23]
	v_mfma_f32_16x16x32_bf16 v[12:15], v[190:193], v[214:217], v[12:15]
	v_mfma_f32_16x16x32_bf16 v[4:7], v[182:185], v[222:225], v[4:7]
	v_mfma_f32_16x16x32_bf16 v[0:3], v[190:193], v[222:225], v[0:3]
	s_barrier
	s_branch .Lpeel_mid_11572

; #define PG8_STAGE(bufoff, gbase, voff, p64) do { _Pragma("unroll") for (int _i = 0; _i < 2; ++_i) { \
;         const char* _gb = (const char*)(gbase) + (size_t)_i * (p64); const unsigned _la = ldsbase + (unsigned)(bufoff) + (unsigned)_i * 8192u; \
;         asm volatile("s_mov_b32 m0, %0\n\ts_nop 0\n\tglobal_load_lds_dwordx4 %1, %2" :: "s"(_la), "v"(voff), "s"(_gb) : "memory"); } } while (0)
; #define PG8_LDA(dst, b, h) do { _Pragma("unroll") for (int m = 0; m < 4; ++m) _Pragma("unroll") for (int k = 0; k < 2; ++k) dst[m][k] = *(const LAS bf16x8*)(lds + PG8_SA(b, h) + aoff + m * 2048 + k * 1024); } while (0)
; #define PG8_LDB(dst, b, h) do { _Pragma("unroll") for (int n = 0; n < 2; ++n) _Pragma("unroll") for (int k = 0; k < 2; ++k) dst[n][k] = *(const LAS bf16x8*)(lds + PG8_SB(b, h) + boff + n * 2048 + k * 1024); } while (0)
; #define PG8_MMA(ai, bj, At, Bt) do { __builtin_amdgcn_s_setprio(1); _Pragma("unroll") for (int m = 0; m < 4; ++m) _Pragma("unroll") for (int n = 0; n < 2; ++n) _Pragma("unroll") for (int k = 0; k < 2; ++k) \
;         acc[ai][bj][m][n] = __builtin_amdgcn_mfma_f32_16x16x32_bf16(Bt[n][k], At[m][k], acc[ai][bj][m][n], 0, 0, 0); __builtin_amdgcn_s_setprio(0); } while (0)
; #define PG8_WAIT_V(n) asm volatile("s_waitcnt vmcnt(" #n ")" ::: "memory")
; #define PG8_WAIT_L(n) asm volatile("s_waitcnt lgkmcnt(" #n ")" ::: "memory")
; #define PG8_BAR __builtin_amdgcn_s_barrier()
; #define PG8_SCHED __builtin_amdgcn_sched_barrier(0)
; template <class Epi, class Sched>
; __device__ __forceinline__ void gemm_phase(LAS unsigned char* lds, const Sched& S, const Epi& E) {
;     ...
;             const bool last = (t == nt - 2);
;             const char* a1 = cA + (size_t)(t + 1) * kstep;
;             const char* a2 = last ? nA : cA + (size_t)(t + 2) * kstep; const char* b2 = last ? nB : cB + (size_t)(t + 2) * kstep;
;             const char* a3 = a2 + kstep; const char* b3 = b2 + kstep;
;             const unsigned vA2 = voffA, vB2 = voffB, hA2 = hA, hB2 = hB;
;             PG8_LDB(B0, 0, 0); PG8_LDB(B1, 0, 1); PG8_SCHED; PG8_LDA(At, 0, 0); PG8_STAGE(PG8_SA(1, 1), a1 + hA, voffA, hA / 2);
;             PG8_WAIT_V(8); PG8_WAIT_L(0); PG8_BAR; PG8_MMA(0, 0, At, B0); PG8_MMA(0, 1, At, B1); PG8_BAR; PG8_SCHED;
.LBB0_581:
	s_add_u32 s62, s16, 0x40080
	s_addc_u32 s63, s17, 0
	s_add_u32 s55, s22, 0x100
	s_addc_u32 s74, s23, 0
	s_mov_b32 s75, -2
	s_waitcnt vmcnt(1)
	s_waitcnt vmcnt(0)
	v_add_u32_e32 v130, 0x10000, v153
	ds_read_b128 v[138:141], v130
	ds_read_b128 v[142:145], v130 offset:1024
	ds_read_b128 v[146:149], v130 offset:2048
	ds_read_b128 v[172:175], v130 offset:3072
	v_add_u32_e32 v130, 0x14000, v153
	ds_read_b128 v[178:181], v130
	ds_read_b128 v[182:185], v130 offset:1024
	ds_read_b128 v[186:189], v130 offset:2048
	ds_read_b128 v[190:193], v130 offset:3072
	s_add_u32 s16, s62, 0xfffc0080
	s_addc_u32 s17, s63, -1
	s_cmp_eq_u32 s75, 12
	s_cselect_b32 s16, s56, s16
	s_cselect_b32 s17, s57, s17
	s_cselect_b32 s72, s58, s55
	s_cselect_b32 s73, s59, s74
	s_add_u32 s22, s16, 0x80
	s_addc_u32 s23, s17, 0
	ds_read_b128 v[194:197], v154
	ds_read_b128 v[198:201], v154 offset:1024
	ds_read_b128 v[202:205], v154 offset:2048
	ds_read_b128 v[206:209], v154 offset:3072
	ds_read_b128 v[210:213], v154 offset:4096
	ds_read_b128 v[214:217], v154 offset:5120
	ds_read_b128 v[218:221], v154 offset:6144
	ds_read_b128 v[222:225], v154 offset:7168
	s_mov_b32 m0, s78
	s_nop 0
	global_load_lds_dwordx4 v128, s[62:63]
	s_add_u32 s82, s62, 0x20000
	s_mov_b32 m0, s80
	s_addc_u32 s83, s63, 0
	global_load_lds_dwordx4 v128, s[82:83]
	s_cmp_eq_u32 s41, 0
	s_cbranch_scc1 .Lpeel_strict_14574_1
	s_waitcnt vmcnt(16) lgkmcnt(0)
	s_branch .Lpeel_join_14574_1

; #define PG8_STAGE(bufoff, gbase, voff, p64) do { _Pragma("unroll") for (int _i = 0; _i < 2; ++_i) { \
;         const char* _gb = (const char*)(gbase) + (size_t)_i * (p64); const unsigned _la = ldsbase + (unsigned)(bufoff) + (unsigned)_i * 8192u; \
;         asm volatile("s_mov_b32 m0, %0\n\ts_nop 0\n\tglobal_load_lds_dwordx4 %1, %2" :: "s"(_la), "v"(voff), "s"(_gb) : "memory"); } } while (0)
; #define PG8_LDA(dst, b, h) do { _Pragma("unroll") for (int m = 0; m < 4; ++m) _Pragma("unroll") for (int k = 0; k < 2; ++k) dst[m][k] = *(const LAS bf16x8*)(lds + PG8_SA(b, h) + aoff + m * 2048 + k * 1024); } while (0)
; #define PG8_MMA(ai, bj, At, Bt) do { __builtin_amdgcn_s_setprio(1); _Pragma("unroll") for (int m = 0; m < 4; ++m) _Pragma("unroll") for (int n = 0; n < 2; ++n) _Pragma("unroll") for (int k = 0; k < 2; ++k) \
;         acc[ai][bj][m][n] = __builtin_amdgcn_mfma_f32_16x16x32_bf16(Bt[n][k], At[m][k], acc[ai][bj][m][n], 0, 0, 0); __builtin_amdgcn_s_setprio(0); } while (0)
; #define PG8_WAIT_V(n) asm volatile("s_waitcnt vmcnt(" #n ")" ::: "memory")
; #define PG8_WAIT_L(n) asm volatile("s_waitcnt lgkmcnt(" #n ")" ::: "memory")
; #define PG8_BAR __builtin_amdgcn_s_barrier()
; #define PG8_SCHED __builtin_amdgcn_sched_barrier(0)
; template <class Epi, class Sched>
; __device__ __forceinline__ void gemm_phase(LAS unsigned char* lds, const Sched& S, const Epi& E) {
;     ...
;             PG8_WAIT_V(8); PG8_WAIT_L(0); PG8_BAR; PG8_MMA(0, 0, At, B0); PG8_MMA(0, 1, At, B1); PG8_BAR; PG8_SCHED;
;             PG8_LDA(At, 0, 1); PG8_STAGE(PG8_SB(0, 0), b2, vB2, hB2 / 2); PG8_STAGE(PG8_SB(0, 1), b2 + hB2, vB2, hB2 / 2); PG8_STAGE(PG8_SA(0, 0), a2, vA2, hA2 / 2);
.Lpeel_join_14574_1:
	s_barrier
	v_mfma_f32_16x16x32_bf16 v[124:127], v[138:141], v[194:197], 0
	v_mfma_f32_16x16x32_bf16 v[120:123], v[146:149], v[194:197], 0
	v_mfma_f32_16x16x32_bf16 v[116:119], v[138:141], v[202:205], 0
	v_mfma_f32_16x16x32_bf16 v[108:111], v[146:149], v[202:205], 0
	v_mfma_f32_16x16x32_bf16 v[100:103], v[138:141], v[210:213], 0
	v_mfma_f32_16x16x32_bf16 v[92:95], v[146:149], v[210:213], 0
	v_mfma_f32_16x16x32_bf16 v[84:87], v[138:141], v[218:221], 0
	v_mfma_f32_16x16x32_bf16 v[76:79], v[146:149], v[218:221], 0
	v_mfma_f32_16x16x32_bf16 v[124:127], v[142:145], v[198:201], v[124:127]
	v_mfma_f32_16x16x32_bf16 v[120:123], v[172:175], v[198:201], v[120:123]
	v_mfma_f32_16x16x32_bf16 v[116:119], v[142:145], v[206:209], v[116:119]
	v_mfma_f32_16x16x32_bf16 v[108:111], v[172:175], v[206:209], v[108:111]
	v_mfma_f32_16x16x32_bf16 v[100:103], v[142:145], v[214:217], v[100:103]
	v_mfma_f32_16x16x32_bf16 v[92:95], v[172:175], v[214:217], v[92:95]
	v_mfma_f32_16x16x32_bf16 v[84:87], v[142:145], v[222:225], v[84:87]
	v_mfma_f32_16x16x32_bf16 v[76:79], v[172:175], v[222:225], v[76:79]
	v_mfma_f32_16x16x32_bf16 v[112:115], v[178:181], v[194:197], 0
	v_mfma_f32_16x16x32_bf16 v[104:107], v[186:189], v[194:197], 0
	v_mfma_f32_16x16x32_bf16 v[96:99], v[178:181], v[202:205], 0
	v_mfma_f32_16x16x32_bf16 v[88:91], v[186:189], v[202:205], 0
	v_mfma_f32_16x16x32_bf16 v[80:83], v[178:181], v[210:213], 0
	v_mfma_f32_16x16x32_bf16 v[72:75], v[186:189], v[210:213], 0
	v_mfma_f32_16x16x32_bf16 v[68:71], v[178:181], v[218:221], 0
	v_mfma_f32_16x16x32_bf16 v[64:67], v[186:189], v[218:221], 0
	v_mfma_f32_16x16x32_bf16 v[112:115], v[182:185], v[198:201], v[112:115]
	v_mfma_f32_16x16x32_bf16 v[104:107], v[190:193], v[198:201], v[104:107]
	v_mfma_f32_16x16x32_bf16 v[96:99], v[182:185], v[206:209], v[96:99]
	v_mfma_f32_16x16x32_bf16 v[88:91], v[190:193], v[206:209], v[88:91]
	v_mfma_f32_16x16x32_bf16 v[80:83], v[182:185], v[214:217], v[80:83]
	v_mfma_f32_16x16x32_bf16 v[72:75], v[190:193], v[214:217], v[72:75]
	v_mfma_f32_16x16x32_bf16 v[68:71], v[182:185], v[222:225], v[68:71]
	v_mfma_f32_16x16x32_bf16 v[64:67], v[190:193], v[222:225], v[64:67]
	s_add_i32 s75, s75, 2
	s_add_u32 s62, s62, 0x100
	s_addc_u32 s63, s63, 0
	s_add_u32 s55, s55, 0x100
	s_addc_u32 s74, s74, 0
	s_barrier
	s_add_u32 s82, s72, 0x20000
	ds_read_b128 v[194:197], v154 offset:16384
	ds_read_b128 v[198:201], v154 offset:17408
	ds_read_b128 v[202:205], v154 offset:18432
	ds_read_b128 v[206:209], v154 offset:19456
	ds_read_b128 v[210:213], v154 offset:20480
	ds_read_b128 v[214:217], v154 offset:21504
	ds_read_b128 v[218:221], v154 offset:22528
	ds_read_b128 v[222:225], v154 offset:23552
	s_mov_b32 m0, s20
	s_nop 0
	global_load_lds_dwordx4 v150, s[72:73]
	s_mov_b32 m0, s24
	s_addc_u32 s83, s73, 0
	global_load_lds_dwordx4 v150, s[82:83]
	s_add_u32 s82, s72, 0x40000
	s_mov_b32 m0, s33
	s_addc_u32 s83, s73, 0
	global_load_lds_dwordx4 v150, s[82:83]
	s_add_u32 s82, s72, 0x60000
	s_mov_b32 m0, s34
	s_addc_u32 s83, s73, 0
	global_load_lds_dwordx4 v150, s[82:83]
	s_mov_b32 m0, s15
	s_nop 0
	global_load_lds_dwordx4 v128, s[16:17]
	s_add_u32 s82, s16, 0x20000
	s_mov_b32 m0, s35
	s_addc_u32 s83, s17, 0
	global_load_lds_dwordx4 v128, s[82:83]
	s_cmp_eq_u32 s41, 0
	s_cbranch_scc1 .Lpeel_strict_14574_0
	s_waitcnt vmcnt(16) lgkmcnt(0)
	s_branch .Lpeel_join_14574_0

; #define PG8_MMA(ai, bj, At, Bt) do { __builtin_amdgcn_s_setprio(1); _Pragma("unroll") for (int m = 0; m < 4; ++m) _Pragma("unroll") for (int n = 0; n < 2; ++n) _Pragma("unroll") for (int k = 0; k < 2; ++k) \
;         acc[ai][bj][m][n] = __builtin_amdgcn_mfma_f32_16x16x32_bf16(Bt[n][k], At[m][k], acc[ai][bj][m][n], 0, 0, 0); __builtin_amdgcn_s_setprio(0); } while (0)
; #define PG8_WAIT_V(n) asm volatile("s_waitcnt vmcnt(" #n ")" ::: "memory")
; #define PG8_WAIT_L(n) asm volatile("s_waitcnt lgkmcnt(" #n ")" ::: "memory")
; #define PG8_BAR __builtin_amdgcn_s_barrier()
; #define PG8_SCHED __builtin_amdgcn_sched_barrier(0)
; template <class Epi, class Sched>
; __device__ __forceinline__ void gemm_phase(LAS unsigned char* lds, const Sched& S, const Epi& E) {
;     ...
;             PG8_WAIT_V(8); PG8_WAIT_L(0); PG8_BAR; PG8_MMA(1, 0, At, B0); PG8_MMA(1, 1, At, B1); PG8_BAR; PG8_SCHED;
.Lpeel_join_14574_0:
	s_barrier
	v_mfma_f32_16x16x32_bf16 v[60:63], v[138:141], v[194:197], 0
	v_mfma_f32_16x16x32_bf16 v[56:59], v[146:149], v[194:197], 0
	v_mfma_f32_16x16x32_bf16 v[52:55], v[138:141], v[202:205], 0
	v_mfma_f32_16x16x32_bf16 v[44:47], v[146:149], v[202:205], 0
	v_mfma_f32_16x16x32_bf16 v[36:39], v[138:141], v[210:213], 0
	v_mfma_f32_16x16x32_bf16 v[28:31], v[146:149], v[210:213], 0
	v_mfma_f32_16x16x32_bf16 v[20:23], v[138:141], v[218:221], 0
	v_mfma_f32_16x16x32_bf16 v[12:15], v[146:149], v[218:221], 0
	v_mfma_f32_16x16x32_bf16 v[60:63], v[142:145], v[198:201], v[60:63]
	v_mfma_f32_16x16x32_bf16 v[56:59], v[172:175], v[198:201], v[56:59]
	v_mfma_f32_16x16x32_bf16 v[52:55], v[142:145], v[206:209], v[52:55]
	v_mfma_f32_16x16x32_bf16 v[44:47], v[172:175], v[206:209], v[44:47]
	v_mfma_f32_16x16x32_bf16 v[36:39], v[142:145], v[214:217], v[36:39]
	v_mfma_f32_16x16x32_bf16 v[28:31], v[172:175], v[214:217], v[28:31]
	v_mfma_f32_16x16x32_bf16 v[20:23], v[142:145], v[222:225], v[20:23]
	v_mfma_f32_16x16x32_bf16 v[12:15], v[172:175], v[222:225], v[12:15]
	v_mfma_f32_16x16x32_bf16 v[48:51], v[178:181], v[194:197], 0
	v_mfma_f32_16x16x32_bf16 v[40:43], v[186:189], v[194:197], 0
	v_mfma_f32_16x16x32_bf16 v[32:35], v[178:181], v[202:205], 0
	v_mfma_f32_16x16x32_bf16 v[24:27], v[186:189], v[202:205], 0
	v_mfma_f32_16x16x32_bf16 v[16:19], v[178:181], v[210:213], 0
	v_mfma_f32_16x16x32_bf16 v[8:11], v[186:189], v[210:213], 0
	v_mfma_f32_16x16x32_bf16 v[4:7], v[178:181], v[218:221], 0
	v_mfma_f32_16x16x32_bf16 v[0:3], v[186:189], v[218:221], 0
	v_mfma_f32_16x16x32_bf16 v[48:51], v[182:185], v[198:201], v[48:51]
	v_mfma_f32_16x16x32_bf16 v[40:43], v[190:193], v[198:201], v[40:43]
	v_mfma_f32_16x16x32_bf16 v[32:35], v[182:185], v[206:209], v[32:35]
	v_mfma_f32_16x16x32_bf16 v[24:27], v[190:193], v[206:209], v[24:27]
	v_mfma_f32_16x16x32_bf16 v[16:19], v[182:185], v[214:217], v[16:19]
	v_mfma_f32_16x16x32_bf16 v[8:11], v[190:193], v[214:217], v[8:11]
	v_mfma_f32_16x16x32_bf16 v[4:7], v[182:185], v[222:225], v[4:7]
	v_mfma_f32_16x16x32_bf16 v[0:3], v[190:193], v[222:225], v[0:3]
	s_barrier
	s_branch .Lpeel_mid_14574

; #define PG8_STAGE(bufoff, gbase, voff, p64) do { _Pragma("unroll") for (int _i = 0; _i < 2; ++_i) { \
;         const char* _gb = (const char*)(gbase) + (size_t)_i * (p64); const unsigned _la = ldsbase + (unsigned)(bufoff) + (unsigned)_i * 8192u; \
;         asm volatile("s_mov_b32 m0, %0\n\ts_nop 0\n\tglobal_load_lds_dwordx4 %1, %2" :: "s"(_la), "v"(voff), "s"(_gb) : "memory"); } } while (0)
; #define PG8_WAIT_V(n) asm volatile("s_waitcnt vmcnt(" #n ")" ::: "memory")
; #define PG8_BAR __builtin_amdgcn_s_barrier()
; template <class Epi, class Sched>
; __device__ __forceinline__ void gemm_phase(LAS unsigned char* lds, const Sched& S, const Epi& E) {
;     ...
;     const int wid = __builtin_amdgcn_readfirstlane(tid >> 6), lane = tid & 63, wr = wid >> 2, wc = wid & 3, fr = lane & 15, fq = lane >> 4;
;     int sR, sRb, sC2;
;     { int R, C; stage_rc(tid * 16, R, C); sR = R; sRb = (R & ~31) + perm32(R & 31); sC2 = C * 2; }
;     const size_t kstep = (size_t)(BK * 2);
;     const unsigned ldsbase = (unsigned)(size_t)lds + (unsigned)wid * 1024u;
;     const int aoff = lds_byte(wr * 64 + fr, fq * 8), boff = lds_byte(wc * 32 + fr, fq * 8);
;     ...
;     int ui = 0;
;     const char* cA; const char* cB; unsigned hA, hB; int nt; unsigned voffA, voffB;
;     { Unit u0; if (!S.next(0, u0)) return;
;       cA = u0.A; cB = u0.B; hA = (unsigned)HALF * u0.lda2; hB = (unsigned)HALF * u0.ldb2; nt = u0.nt;
;       voffA = (unsigned)(sR * u0.lda2 + sC2); voffB = (unsigned)(sRb * u0.ldb2 + sC2); }
;     f32x4 acc[2][2][4][2];
; #pragma unroll
;     for (int a = 0; a < 2; ++a)
; #pragma unroll
;         for (int b = 0; b < 2; ++b)
; #pragma unroll
;             for (int m = 0; m < 4; ++m)
; #pragma unroll
;                 for (int n = 0; n < 2; ++n) acc[a][b][m][n] = (f32x4){0.f, 0.f, 0.f, 0.f};
;     bf16x8 At[4][2], B0[2][2], B1[2][2];
;     PG8_STAGE(PG8_SB(0, 0), cB, voffB, hB / 2); PG8_STAGE(PG8_SB(0, 1), cB + hB, voffB, hB / 2); PG8_STAGE(PG8_SA(0, 0), cA, voffA, hA / 2); PG8_STAGE(PG8_SA(0, 1), cA + hA, voffA, hA / 2);
;     if (wr == 1) PG8_BAR;
;     PG8_WAIT_V(2); PG8_BAR;
;     PG8_STAGE(PG8_SB(1, 0), cB + kstep, voffB, hB / 2); PG8_STAGE(PG8_SA(1, 0), cA + kstep, voffA, hA / 2); PG8_STAGE(PG8_SB(1, 1), cB + hB + kstep, voffB, hB / 2);
;     PG8_WAIT_V(6); PG8_BAR;
.LBB0_747:
	v_bfe_u32 v145, v0, 4, 2
	v_and_b32_e32 v144, 15, v0
	v_lshlrev_b32_e32 v1, 4, v145
	v_lshlrev_b32_e32 v0, 2, v0
	s_and_b32 s30, s10, 3
	s_lshl_b32 s42, s9, 6
	v_lshl_or_b32 v1, v144, 6, v1
	s_lshl_b32 s9, s9, 13
	v_and_b32_e32 v0, 32, v0
	v_bitop3_b32 v2, v1, s9, v0 bitop3:0xde
	s_lshl_b32 s44, s30, 5
	s_lshl_b32 s9, s30, 12
	s_add_u32 s10, s16, 0x80
	s_addc_u32 s11, s17, 0
	s_add_i32 s45, s15, 0x18000
	s_waitcnt vmcnt(2)
	s_barrier
	s_mov_b32 m0, s45
	s_nop 0
	global_load_lds_dwordx4 v143, s[10:11]
	s_add_u32 s10, s16, 0x20080
	s_addc_u32 s11, s17, 0
	s_add_i32 s47, s15, 0x1a000
	s_mov_b32 m0, s47
	s_nop 0
	global_load_lds_dwordx4 v143, s[10:11]
	s_add_u32 s10, s22, 0x80
	s_addc_u32 s11, s23, 0
	s_add_i32 s48, s15, 0x8000
	s_mov_b32 m0, s48
	s_nop 0
	global_load_lds_dwordx4 v142, s[10:11]
	s_add_u32 s10, s22, 0x20080
	s_addc_u32 s11, s23, 0
	s_add_i32 s50, s15, 0xa000
	s_mov_b32 m0, s50
	s_nop 0
	global_load_lds_dwordx4 v142, s[10:11]
	s_add_u32 s10, s16, 0x40080
	s_addc_u32 s11, s17, 0
	s_add_i32 s51, s15, 0x1c000
	s_mov_b32 m0, s51
	s_nop 0
	global_load_lds_dwordx4 v143, s[10:11]
	s_add_u32 s10, s16, 0x60080
	s_addc_u32 s11, s17, 0
	s_add_i32 s61, s15, 0x1e000
	s_mov_b32 m0, s61
	s_nop 0
	global_load_lds_dwordx4 v143, s[10:11]
	s_add_i32 s62, s15, 0xc000
	s_waitcnt vmcnt(6)
	s_cmpk_lt_u32 s8, 0x100
	v_bitop3_b32 v0, v1, s9, v0 bitop3:0xde
	s_cselect_b64 s[38:39], -1, 0
	s_cmp_gt_u32 s30, 1
	s_cselect_b64 s[8:9], -1, 0
	s_add_i32 s63, s15, 0xe000
	s_mov_b32 s68, 0
	v_add_u32_e32 v146, 0, v0
	v_add_u32_e32 v147, 0, v2
	s_lshl_b32 s64, s44, 1
	s_mov_b64 s[54:55], s[16:17]
	s_mov_b64 s[40:41], s[22:23]
	s_barrier
	s_waitcnt vmcnt(0)
	s_mov_b32 s99, -1
	s_branch .LBB0_750

; __device__ __forceinline__ bool tile_of(long Lidx, int nM, int nN, int& pm, int& pn) {
;     const int nwg = nM * nN; if (Lidx >= nwg) return false;
;     int wgid = (int)Lidx; { const int q = nwg / NXCD, r = nwg % NXCD, xcd = wgid % NXCD, off = wgid / NXCD; wgid = (xcd < r ? xcd * (q + 1) : r * (q + 1) + (xcd - r) * q) + off; }
;     const int nig = WGM * nN, gid = wgid / nig, fm = gid * WGM, gsz = (nM - fm) < WGM ? (nM - fm) : WGM;
;     pm = fm + ((wgid % nig) % gsz); pn = (wgid % nig) / gsz; return true;
; }
; template <class Epi, class Sched>
; __device__ __forceinline__ void gemm_phase(LAS unsigned char* lds, const Sched& S, const Epi& E) {
;     ...
;         const char* nA = cA; const char* nB = cB; int nnt = nt; bool has_next;
;         { Unit nx; has_next = S.next(ui + 1, nx);
;           if (has_next) { nA = nx.A; nB = nx.B; nnt = nx.nt; } }
.LBB0_750:
	s_mov_b32 s100, s98
	s_mov_b32 s101, s99
	s_add_i32 s65, s68, 1
	s_mul_i32 s10, s65, s29
	s_mul_hi_u32 s11, s65, s28
	s_add_i32 s11, s11, s10
	s_mul_i32 s10, s65, s28
	s_add_u32 s56, s10, s2
	s_addc_u32 s57, s11, s3
	v_mov_b64_e32 v[0:1], 0x200
	v_cmp_lt_i64_e64 s[10:11], s[56:57], v[0:1]
	v_mov_b64_e32 v[0:1], 0x1ff
	v_cmp_gt_i64_e32 vcc, s[56:57], v[0:1]
	s_cbranch_vccnz .LBB0_756
	s_ashr_i32 s30, s56, 31
	s_lshr_b32 s30, s30, 29
	s_add_i32 s54, s56, s30
	s_and_b32 s30, s54, -8
	s_sub_i32 s55, s56, s30
	s_cmp_gt_i32 s55, -1
	s_mov_b64 s[40:41], -1
	s_cbranch_scc0 .LBB0_753
	s_lshl_b32 s56, s55, 6
	s_mov_b64 s[40:41], 0

; #define PG8_STAGE(bufoff, gbase, voff, p64) do { _Pragma("unroll") for (int _i = 0; _i < 2; ++_i) { \
;         const char* _gb = (const char*)(gbase) + (size_t)_i * (p64); const unsigned _la = ldsbase + (unsigned)(bufoff) + (unsigned)_i * 8192u; \
;         asm volatile("s_mov_b32 m0, %0\n\ts_nop 0\n\tglobal_load_lds_dwordx4 %1, %2" :: "s"(_la), "v"(voff), "s"(_gb) : "memory"); } } while (0)
; #define PG8_LDA(dst, b, h) do { _Pragma("unroll") for (int m = 0; m < 4; ++m) _Pragma("unroll") for (int k = 0; k < 2; ++k) dst[m][k] = *(const LAS bf16x8*)(lds + PG8_SA(b, h) + aoff + m * 2048 + k * 1024); } while (0)
; #define PG8_LDB(dst, b, h) do { _Pragma("unroll") for (int n = 0; n < 2; ++n) _Pragma("unroll") for (int k = 0; k < 2; ++k) dst[n][k] = *(const LAS bf16x8*)(lds + PG8_SB(b, h) + boff + n * 2048 + k * 1024); } while (0)
; #define PG8_BAR __builtin_amdgcn_s_barrier()
; __device__ __forceinline__ bool tile_of(long Lidx, int nM, int nN, int& pm, int& pn) {
;     ...
;     int wgid = (int)Lidx; { const int q = nwg / NXCD, r = nwg % NXCD, xcd = wgid % NXCD, off = wgid / NXCD; wgid = (xcd < r ? xcd * (q + 1) : r * (q + 1) + (xcd - r) * q) + off; }
;     const int nig = WGM * nN, gid = wgid / nig, fm = gid * WGM, gsz = (nM - fm) < WGM ? (nM - fm) : WGM;
;     pm = fm + ((wgid % nig) % gsz); pn = (wgid % nig) / gsz; return true;
; }
; template <class Epi, class Sched>
; __device__ __forceinline__ void gemm_phase(LAS unsigned char* lds, const Sched& S, const Epi& E) {
;     ...
;             const bool last = (t == nt - 2);
;             const char* a1 = cA + (size_t)(t + 1) * kstep;
;             const char* a2 = last ? nA : cA + (size_t)(t + 2) * kstep; const char* b2 = last ? nB : cB + (size_t)(t + 2) * kstep;
;             const char* a3 = a2 + kstep; const char* b3 = b2 + kstep;
;             const unsigned vA2 = voffA, vB2 = voffB, hA2 = hA, hB2 = hB;
;             PG8_LDB(B0, 0, 0); PG8_LDB(B1, 0, 1); PG8_SCHED; PG8_LDA(At, 0, 0); PG8_STAGE(PG8_SA(1, 1), a1 + hA, voffA, hA / 2);
;             PG8_WAIT_V(8); PG8_WAIT_L(0); PG8_BAR; PG8_MMA(0, 0, At, B0); PG8_MMA(0, 1, At, B1); PG8_BAR; PG8_SCHED;
;     __device__ __forceinline__ bool next(int i, Unit& u) const {
;     ...
;         u.A = A + (size_t)pm * 256 * lda2; u.B = B + (size_t)pn * 256 * ldb2; u.lda2 = lda2; u.ldb2 = ldb2; u.nt = nt; u.kind = 0; u.pm = pm; u.pn = pn; u.z = 0; u.w = 0; return true;
.LBB0_755:
	s_ashr_i32 s30, s54, 3
	s_add_i32 s30, s56, s30
	s_ashr_i32 s31, s30, 31
	s_lshr_b32 s31, s31, 26
	s_add_i32 s31, s30, s31
	s_ashr_i32 s40, s31, 6
	s_lshl_b32 s40, s40, 3
	s_sub_i32 s41, 64, s40
	s_min_i32 s41, s41, 8
	s_andn2_b32 s31, s31, 63
	s_sub_i32 s30, s30, s31
	s_ashr_i32 s54, s30, 3
	s_mul_i32 s31, s54, s41
	s_sub_i32 s30, s30, s31
	s_add_i32 s40, s40, s30
	s_mov_b32 s98, s40
	s_mov_b32 s99, s54
	s_ashr_i32 s41, s40, 31
	s_lshl_b64 s[40:41], s[40:41], 19
	s_add_u32 s40, s4, s40
	s_addc_u32 s41, s5, s41
	s_ashr_i32 s55, s54, 31
	s_lshl_b64 s[54:55], s[54:55], 19
	s_add_u32 s54, s12, s54
	s_addc_u32 s55, s14, s55
.LBB0_756:
	s_add_u32 s56, s22, 0x40080
	s_addc_u32 s57, s23, 0
	s_add_u32 s69, s16, 0x100
	s_addc_u32 s72, s17, 0
	s_mov_b32 s73, -2
	v_add_u32_e32 v128, 0x10000, v146
	ds_read_b128 v[130:133], v128
	ds_read_b128 v[134:137], v128 offset:1024
	ds_read_b128 v[138:141], v128 offset:2048
	ds_read_b128 v[148:151], v128 offset:3072
	v_add_u32_e32 v128, 0x14000, v146
	ds_read_b128 v[152:155], v128
	ds_read_b128 v[158:161], v128 offset:1024
	ds_read_b128 v[162:165], v128 offset:2048
	ds_read_b128 v[172:175], v128 offset:3072
	s_add_u32 s16, s56, 0xfffc0080
	s_addc_u32 s17, s57, -1
	s_cmp_eq_u32 s73, 12
	s_cselect_b32 s16, s40, s16
	s_cselect_b32 s17, s41, s17
	s_cselect_b32 s58, s54, s69
	s_cselect_b32 s59, s55, s72
	s_add_u32 s22, s16, 0x80
	s_addc_u32 s23, s17, 0
	ds_read_b128 v[178:181], v147
	ds_read_b128 v[182:185], v147 offset:1024
	ds_read_b128 v[186:189], v147 offset:2048
	ds_read_b128 v[190:193], v147 offset:3072
	ds_read_b128 v[194:197], v147 offset:4096
	ds_read_b128 v[198:201], v147 offset:5120
	ds_read_b128 v[202:205], v147 offset:6144
	ds_read_b128 v[206:209], v147 offset:7168
	s_mov_b32 m0, s62
	s_nop 0
	global_load_lds_dwordx4 v142, s[56:57]
	s_add_u32 s74, s56, 0x20000
	s_mov_b32 m0, s63
	s_addc_u32 s75, s57, 0
	global_load_lds_dwordx4 v142, s[74:75]
	s_cmp_eq_u32 s68, 0
	s_cbranch_scc1 .Lpeel_strict_20367_1
	s_waitcnt vmcnt(24) lgkmcnt(0)
	s_branch .Lpeel_join_20367_1

; #define PG8_STAGE(bufoff, gbase, voff, p64) do { _Pragma("unroll") for (int _i = 0; _i < 2; ++_i) { \
;         const char* _gb = (const char*)(gbase) + (size_t)_i * (p64); const unsigned _la = ldsbase + (unsigned)(bufoff) + (unsigned)_i * 8192u; \
;         asm volatile("s_mov_b32 m0, %0\n\ts_nop 0\n\tglobal_load_lds_dwordx4 %1, %2" :: "s"(_la), "v"(voff), "s"(_gb) : "memory"); } } while (0)
; #define PG8_LDA(dst, b, h) do { _Pragma("unroll") for (int m = 0; m < 4; ++m) _Pragma("unroll") for (int k = 0; k < 2; ++k) dst[m][k] = *(const LAS bf16x8*)(lds + PG8_SA(b, h) + aoff + m * 2048 + k * 1024); } while (0)
; #define PG8_MMA(ai, bj, At, Bt) do { __builtin_amdgcn_s_setprio(1); _Pragma("unroll") for (int m = 0; m < 4; ++m) _Pragma("unroll") for (int n = 0; n < 2; ++n) _Pragma("unroll") for (int k = 0; k < 2; ++k) \
;         acc[ai][bj][m][n] = __builtin_amdgcn_mfma_f32_16x16x32_bf16(Bt[n][k], At[m][k], acc[ai][bj][m][n], 0, 0, 0); __builtin_amdgcn_s_setprio(0); } while (0)
; #define PG8_WAIT_V(n) asm volatile("s_waitcnt vmcnt(" #n ")" ::: "memory")
; #define PG8_WAIT_L(n) asm volatile("s_waitcnt lgkmcnt(" #n ")" ::: "memory")
; #define PG8_BAR __builtin_amdgcn_s_barrier()
; #define PG8_SCHED __builtin_amdgcn_sched_barrier(0)
; template <class Epi, class Sched>
; __device__ __forceinline__ void gemm_phase(LAS unsigned char* lds, const Sched& S, const Epi& E) {
;     ...
;             PG8_WAIT_V(8); PG8_WAIT_L(0); PG8_BAR; PG8_MMA(0, 0, At, B0); PG8_MMA(0, 1, At, B1); PG8_BAR; PG8_SCHED;
;             PG8_LDA(At, 0, 1); PG8_STAGE(PG8_SB(0, 0), b2, vB2, hB2 / 2); PG8_STAGE(PG8_SB(0, 1), b2 + hB2, vB2, hB2 / 2); PG8_STAGE(PG8_SA(0, 0), a2, vA2, hA2 / 2);
.Lpeel_join_20367_1:
	s_barrier
	v_mfma_f32_16x16x32_bf16 v[124:127], v[130:133], v[178:181], 0
	v_mfma_f32_16x16x32_bf16 v[116:119], v[138:141], v[178:181], 0
	v_mfma_f32_16x16x32_bf16 v[108:111], v[130:133], v[186:189], 0
	v_mfma_f32_16x16x32_bf16 v[100:103], v[138:141], v[186:189], 0
	v_mfma_f32_16x16x32_bf16 v[92:95], v[130:133], v[194:197], 0
	v_mfma_f32_16x16x32_bf16 v[84:87], v[138:141], v[194:197], 0
	v_mfma_f32_16x16x32_bf16 v[76:79], v[130:133], v[202:205], 0
	v_mfma_f32_16x16x32_bf16 v[68:71], v[138:141], v[202:205], 0
	v_mfma_f32_16x16x32_bf16 v[124:127], v[134:137], v[182:185], v[124:127]
	v_mfma_f32_16x16x32_bf16 v[116:119], v[148:151], v[182:185], v[116:119]
	v_mfma_f32_16x16x32_bf16 v[108:111], v[134:137], v[190:193], v[108:111]
	v_mfma_f32_16x16x32_bf16 v[100:103], v[148:151], v[190:193], v[100:103]
	v_mfma_f32_16x16x32_bf16 v[92:95], v[134:137], v[198:201], v[92:95]
	v_mfma_f32_16x16x32_bf16 v[84:87], v[148:151], v[198:201], v[84:87]
	v_mfma_f32_16x16x32_bf16 v[76:79], v[134:137], v[206:209], v[76:79]
	v_mfma_f32_16x16x32_bf16 v[68:71], v[148:151], v[206:209], v[68:71]
	v_mfma_f32_16x16x32_bf16 v[120:123], v[152:155], v[178:181], 0
	v_mfma_f32_16x16x32_bf16 v[112:115], v[162:165], v[178:181], 0
	v_mfma_f32_16x16x32_bf16 v[104:107], v[152:155], v[186:189], 0
	v_mfma_f32_16x16x32_bf16 v[96:99], v[162:165], v[186:189], 0
	v_mfma_f32_16x16x32_bf16 v[88:91], v[152:155], v[194:197], 0
	v_mfma_f32_16x16x32_bf16 v[80:83], v[162:165], v[194:197], 0
	v_mfma_f32_16x16x32_bf16 v[72:75], v[152:155], v[202:205], 0
	v_mfma_f32_16x16x32_bf16 v[64:67], v[162:165], v[202:205], 0
	v_mfma_f32_16x16x32_bf16 v[120:123], v[158:161], v[182:185], v[120:123]
	v_mfma_f32_16x16x32_bf16 v[112:115], v[172:175], v[182:185], v[112:115]
	v_mfma_f32_16x16x32_bf16 v[104:107], v[158:161], v[190:193], v[104:107]
	v_mfma_f32_16x16x32_bf16 v[96:99], v[172:175], v[190:193], v[96:99]
	v_mfma_f32_16x16x32_bf16 v[88:91], v[158:161], v[198:201], v[88:91]
	v_mfma_f32_16x16x32_bf16 v[80:83], v[172:175], v[198:201], v[80:83]
	v_mfma_f32_16x16x32_bf16 v[72:75], v[158:161], v[206:209], v[72:75]
	v_mfma_f32_16x16x32_bf16 v[64:67], v[172:175], v[206:209], v[64:67]
	s_add_i32 s73, s73, 2
	s_add_u32 s56, s56, 0x100
	s_addc_u32 s57, s57, 0
	s_add_u32 s69, s69, 0x100
	s_addc_u32 s72, s72, 0
	s_barrier
	s_add_u32 s74, s58, 0x20000
	ds_read_b128 v[178:181], v147 offset:16384
	ds_read_b128 v[182:185], v147 offset:17408
	ds_read_b128 v[186:189], v147 offset:18432
	ds_read_b128 v[190:193], v147 offset:19456
	ds_read_b128 v[194:197], v147 offset:20480
	ds_read_b128 v[198:201], v147 offset:21504
	ds_read_b128 v[202:205], v147 offset:22528
	ds_read_b128 v[206:209], v147 offset:23552
	s_mov_b32 m0, s20
	s_nop 0
	global_load_lds_dwordx4 v143, s[58:59]
	s_mov_b32 m0, s24
	s_addc_u32 s75, s59, 0
	global_load_lds_dwordx4 v143, s[74:75]
	s_add_u32 s74, s58, 0x40000
	s_mov_b32 m0, s33
	s_addc_u32 s75, s59, 0
	global_load_lds_dwordx4 v143, s[74:75]
	s_add_u32 s74, s58, 0x60000
	s_mov_b32 m0, s34
	s_addc_u32 s75, s59, 0
	global_load_lds_dwordx4 v143, s[74:75]
	s_mov_b32 m0, s15
	s_nop 0
	global_load_lds_dwordx4 v142, s[16:17]
	s_add_u32 s74, s16, 0x20000
	s_mov_b32 m0, s35
	s_addc_u32 s75, s17, 0
	global_load_lds_dwordx4 v142, s[74:75]
	s_cmp_eq_u32 s68, 0
	s_cbranch_scc1 .Lpeel_strict_20367_0
	s_waitcnt vmcnt(24) lgkmcnt(0)
	s_branch .Lpeel_join_20367_0

; #define PG8_MMA(ai, bj, At, Bt) do { __builtin_amdgcn_s_setprio(1); _Pragma("unroll") for (int m = 0; m < 4; ++m) _Pragma("unroll") for (int n = 0; n < 2; ++n) _Pragma("unroll") for (int k = 0; k < 2; ++k) \
;         acc[ai][bj][m][n] = __builtin_amdgcn_mfma_f32_16x16x32_bf16(Bt[n][k], At[m][k], acc[ai][bj][m][n], 0, 0, 0); __builtin_amdgcn_s_setprio(0); } while (0)
; #define PG8_WAIT_V(n) asm volatile("s_waitcnt vmcnt(" #n ")" ::: "memory")
; #define PG8_WAIT_L(n) asm volatile("s_waitcnt lgkmcnt(" #n ")" ::: "memory")
; #define PG8_BAR __builtin_amdgcn_s_barrier()
; #define PG8_SCHED __builtin_amdgcn_sched_barrier(0)
; template <class Epi, class Sched>
; __device__ __forceinline__ void gemm_phase(LAS unsigned char* lds, const Sched& S, const Epi& E) {
;     ...
;             PG8_WAIT_V(8); PG8_WAIT_L(0); PG8_BAR; PG8_MMA(1, 0, At, B0); PG8_MMA(1, 1, At, B1); PG8_BAR; PG8_SCHED;
.Lpeel_join_20367_0:
	s_barrier
	v_mfma_f32_16x16x32_bf16 v[60:63], v[130:133], v[178:181], 0
	v_mfma_f32_16x16x32_bf16 v[52:55], v[138:141], v[178:181], 0
	v_mfma_f32_16x16x32_bf16 v[44:47], v[130:133], v[186:189], 0
	v_mfma_f32_16x16x32_bf16 v[36:39], v[138:141], v[186:189], 0
	v_mfma_f32_16x16x32_bf16 v[28:31], v[130:133], v[194:197], 0
	v_mfma_f32_16x16x32_bf16 v[20:23], v[138:141], v[194:197], 0
	v_mfma_f32_16x16x32_bf16 v[12:15], v[130:133], v[202:205], 0
	v_mfma_f32_16x16x32_bf16 v[4:7], v[138:141], v[202:205], 0
	v_mfma_f32_16x16x32_bf16 v[60:63], v[134:137], v[182:185], v[60:63]
	v_mfma_f32_16x16x32_bf16 v[52:55], v[148:151], v[182:185], v[52:55]
	v_mfma_f32_16x16x32_bf16 v[44:47], v[134:137], v[190:193], v[44:47]
	v_mfma_f32_16x16x32_bf16 v[36:39], v[148:151], v[190:193], v[36:39]
	v_mfma_f32_16x16x32_bf16 v[28:31], v[134:137], v[198:201], v[28:31]
	v_mfma_f32_16x16x32_bf16 v[20:23], v[148:151], v[198:201], v[20:23]
	v_mfma_f32_16x16x32_bf16 v[12:15], v[134:137], v[206:209], v[12:15]
	v_mfma_f32_16x16x32_bf16 v[4:7], v[148:151], v[206:209], v[4:7]
	v_mfma_f32_16x16x32_bf16 v[56:59], v[152:155], v[178:181], 0
	v_mfma_f32_16x16x32_bf16 v[48:51], v[162:165], v[178:181], 0
	v_mfma_f32_16x16x32_bf16 v[40:43], v[152:155], v[186:189], 0
	v_mfma_f32_16x16x32_bf16 v[32:35], v[162:165], v[186:189], 0
	v_mfma_f32_16x16x32_bf16 v[24:27], v[152:155], v[194:197], 0
	v_mfma_f32_16x16x32_bf16 v[16:19], v[162:165], v[194:197], 0
	v_mfma_f32_16x16x32_bf16 v[8:11], v[152:155], v[202:205], 0
	v_mfma_f32_16x16x32_bf16 v[0:3], v[162:165], v[202:205], 0
	v_mfma_f32_16x16x32_bf16 v[56:59], v[158:161], v[182:185], v[56:59]
	v_mfma_f32_16x16x32_bf16 v[48:51], v[172:175], v[182:185], v[48:51]
	v_mfma_f32_16x16x32_bf16 v[40:43], v[158:161], v[190:193], v[40:43]
	v_mfma_f32_16x16x32_bf16 v[32:35], v[172:175], v[190:193], v[32:35]
	v_mfma_f32_16x16x32_bf16 v[24:27], v[158:161], v[198:201], v[24:27]
	v_mfma_f32_16x16x32_bf16 v[16:19], v[172:175], v[198:201], v[16:19]
	v_mfma_f32_16x16x32_bf16 v[8:11], v[158:161], v[206:209], v[8:11]
	v_mfma_f32_16x16x32_bf16 v[0:3], v[172:175], v[206:209], v[0:3]
	s_barrier
	s_branch .Lpeel_mid_20367

; __device__ __forceinline__ bool tile_of(long Lidx, int nM, int nN, int& pm, int& pn) {
;     const int nwg = nM * nN; if (Lidx >= nwg) return false;
;     int wgid = (int)Lidx; { const int q = nwg / NXCD, r = nwg % NXCD, xcd = wgid % NXCD, off = wgid / NXCD; wgid = (xcd < r ? xcd * (q + 1) : r * (q + 1) + (xcd - r) * q) + off; }
;     const int nig = WGM * nN, gid = wgid / nig, fm = gid * WGM, gsz = (nM - fm) < WGM ? (nM - fm) : WGM;
;     pm = fm + ((wgid % nig) % gsz); pn = (wgid % nig) / gsz; return true;
; }
; template <class Epi, class Sched>
; __device__ __forceinline__ void gemm_phase(LAS unsigned char* lds, const Sched& S, const Epi& E) {
;     ...
;         { int efr = fr, efq = fq, eui = ui; asm volatile("" : "+v"(efr), "+v"(efq), "+s"(eui));
;           Unit eu; S.next(eui, eu); keep = E(acc, eu, wr, wc, efr, efq); }
;     __device__ __forceinline__ bool next(int i, Unit& u) const {
;         int pm, pn; if (!tile_of((long)i * G + c, nM, nN, pm, pn)) return false;
;         u.A = A + (size_t)pm * 256 * lda2; u.B = B + (size_t)pn * 256 * ldb2; u.lda2 = lda2; u.ldb2 = ldb2; u.nt = nt; u.kind = 0; u.pm = pm; u.pn = pn; u.z = 0; u.w = 0; return true;
.LBB0_760:
	v_mov_b32_e32 v128, v145
	v_mov_b32_e32 v140, v144
	v_mov_b32_e32 v132, s28
	v_mov_b64_e32 v[130:131], s[2:3]
	s_mov_b64 s[22:23], 0x1ff
	v_mad_i64_i32 v[130:131], s[16:17], s68, v132, v[130:131]
	v_cmp_lt_i64_e32 vcc, s[22:23], v[130:131]
	v_readfirstlane_b32 s16, v130
	s_cbranch_vccnz .LBB0_766
	s_cmp_lt_i32 s101, 0
	s_cbranch_scc1 .Lcalc_full_1
	s_mov_b32 s67, s100
	s_mov_b32 s66, s101
	s_branch .LBB0_766
.Lcalc_full_1:
	s_ashr_i32 s17, s16, 31
	s_lshr_b32 s17, s17, 29
	s_add_i32 s22, s16, s17
	s_and_b32 s17, s22, -8
	s_sub_i32 s23, s16, s17
	s_cmp_gt_i32 s23, -1
	s_mov_b64 s[16:17], -1
	s_cbranch_scc0 .LBB0_763
	s_lshl_b32 s56, s23, 6
	s_mov_b64 s[16:17], 0
